# prep_conv row-major path: weight/bias loads hoisted next to the tile loads, issued once per item
# baseline (speedup 1.0000x reference)
.LBB0_668:
	s_and_b64 vcc, exec, s[38:39]
	s_cbranch_vccz .LBB0_674
	s_add_i32 s38, s60, 0xfffffcd0
	s_lshr_b32 s54, s38, 4
	s_and_b32 s47, s60, 15
	v_mov_b32_e32 v3, v206
	s_movk_i32 s39, 0x840
	s_lshl_b32 s35, s54, 7
	s_lshl_b32 s37, s47, 6
	v_cmp_gt_i32_e32 vcc, s39, v3
	s_and_saveexec_b64 s[48:49], vcc
	s_cbranch_execz .LBB0_695
	s_and_b32 s39, s35, 0xf00
	s_and_b32 s51, s35, 0x1c00
	s_add_i32 s50, s39, 0x100
	s_add_i32 s55, s51, 0x400
	s_cmpk_lt_u32 s38, 0x200
	s_cselect_b32 s55, s50, s55
	s_cselect_b32 s56, s39, s51
	s_add_i32 s57, s35, -2
	s_lshl_b32 s92, s37, 2
	v_and_b32_e32 v120, 15, v206
	v_lshlrev_b32_e32 v121, 4, v120
	v_ashrrev_i32_e32 v122, 4, v206
	v_add_u32_e32 v123, s57, v122
	s_add_u32 s4, s92, 0x3a24800
	v_add_u32_e32 v124, s4, v121
	s_movk_i32 s5, 0x2440
	v_mul_u32_u24_e32 v125, 0x104, v122
	v_add_u32_e32 v125, v125, v121
	s_mov_b64 s[58:59], exec
	v_mov_b32_e32 v126, v123
	v_cmp_le_i32_e32 vcc, s56, v126
	v_cmp_gt_i32_e64 s[38:39], s55, v126
	v_mov_b32_e32 v100, 0
	v_mov_b32_e32 v101, 0
	v_mov_b32_e32 v102, 0
	v_mov_b32_e32 v103, 0
	s_and_b64 s[38:39], vcc, s[38:39]
	v_mul_lo_u32 v127, v126, s5
	v_add_u32_e32 v127, v127, v124
	s_and_b64 exec, s[58:59], s[38:39]
	global_load_dwordx4 v[100:103], v127, s[96:97]
	s_mov_b64 exec, s[58:59]
	v_add_u32_e32 v126, 32, v123
	v_cmp_le_i32_e32 vcc, s56, v126
	v_cmp_gt_i32_e64 s[38:39], s55, v126
	v_mov_b32_e32 v104, 0
	v_mov_b32_e32 v105, 0
	v_mov_b32_e32 v106, 0
	v_mov_b32_e32 v107, 0
	s_and_b64 s[38:39], vcc, s[38:39]
	v_mul_lo_u32 v127, v126, s5
	v_add_u32_e32 v127, v127, v124
	s_and_b64 exec, s[58:59], s[38:39]
	global_load_dwordx4 v[104:107], v127, s[96:97]
	s_mov_b64 exec, s[58:59]
	v_add_u32_e32 v126, 64, v123
	v_cmp_le_i32_e32 vcc, s56, v126
	v_cmp_gt_i32_e64 s[38:39], s55, v126
	v_mov_b32_e32 v108, 0
	v_mov_b32_e32 v109, 0
	v_mov_b32_e32 v110, 0
	v_mov_b32_e32 v111, 0
	s_and_b64 s[38:39], vcc, s[38:39]
	v_mul_lo_u32 v127, v126, s5
	v_add_u32_e32 v127, v127, v124
	s_and_b64 exec, s[58:59], s[38:39]
	global_load_dwordx4 v[108:111], v127, s[96:97]
	s_mov_b64 exec, s[58:59]
	v_add_u32_e32 v126, 96, v123
	v_cmp_le_i32_e32 vcc, s56, v126
	v_cmp_gt_i32_e64 s[38:39], s55, v126
	v_mov_b32_e32 v112, 0
	v_mov_b32_e32 v113, 0
	v_mov_b32_e32 v114, 0
	v_mov_b32_e32 v115, 0
	s_and_b64 s[38:39], vcc, s[38:39]
	v_mul_lo_u32 v127, v126, s5
	v_add_u32_e32 v127, v127, v124
	s_and_b64 exec, s[58:59], s[38:39]
	global_load_dwordx4 v[112:115], v127, s[96:97]
	s_mov_b64 exec, s[58:59]
	v_add_u32_e32 v126, 128, v123
	v_cmp_le_i32_e32 vcc, s56, v126
	v_cmp_gt_i32_e64 s[38:39], s55, v126
	v_mov_b32_e32 v116, 0
	v_mov_b32_e32 v117, 0
	v_mov_b32_e32 v118, 0
	v_mov_b32_e32 v119, 0
	s_and_b64 s[38:39], vcc, s[38:39]
	v_cmp_gt_u32_e64 s[50:51], 64, v206
	v_mul_lo_u32 v127, v126, s5
	s_and_b64 s[38:39], s[38:39], s[50:51]
	v_add_u32_e32 v127, v127, v124
	s_and_b64 exec, s[58:59], s[38:39]
	global_load_dwordx4 v[116:119], v127, s[96:97]
	s_mov_b64 exec, s[58:59]
	s_cmp_lt_u32 s47, 8
	s_cbranch_scc1 .Lcvw_skip
	v_and_b32_e32 v128, 7, v206
	v_lshlrev_b32_e32 v128, 5, v128
	v_add_u32_e32 v128, s92, v128
	global_load_dwordx4 v[130:133], v128, s[40:41]
	global_load_dwordx4 v[134:137], v128, s[40:41] offset:16
	v_add_u32_e32 v129, 0x1000, v128
	global_load_dwordx4 v[138:141], v129, s[40:41]
	global_load_dwordx4 v[142:145], v129, s[40:41] offset:16
	v_add_u32_e32 v129, 0x2000, v128
	global_load_dwordx4 v[146:149], v129, s[40:41]
	global_load_dwordx4 v[150:153], v129, s[40:41] offset:16
	v_add_u32_e32 v129, 0x3000, v128
	global_load_dwordx4 v[154:157], v129, s[40:41]
	global_load_dwordx4 v[158:161], v129, s[40:41] offset:16
	v_add_u32_e32 v129, 0x4000, v128
	global_load_dwordx4 v[162:165], v129, s[40:41]
	global_load_dwordx4 v[166:169], v129, s[40:41] offset:16
	global_load_dwordx4 v[170:173], v128, s[42:43]
	global_load_dwordx4 v[174:177], v128, s[42:43] offset:16
.Lcvw_skip:
	s_waitcnt vmcnt(0)
	ds_write2_b32 v125, v100, v101 offset1:1
	ds_write2_b32 v125, v102, v103 offset0:2 offset1:3
	v_add_u32_e32 v126, 0x2080, v125
	ds_write2_b32 v126, v104, v105 offset1:1
	ds_write2_b32 v126, v106, v107 offset0:2 offset1:3
	v_add_u32_e32 v126, 0x4100, v125
	ds_write2_b32 v126, v108, v109 offset1:1
	ds_write2_b32 v126, v110, v111 offset0:2 offset1:3
	v_add_u32_e32 v126, 0x6180, v125
	ds_write2_b32 v126, v112, v113 offset1:1
	ds_write2_b32 v126, v114, v115 offset0:2 offset1:3
	s_and_b64 exec, s[58:59], s[50:51]
	v_add_u32_e32 v126, 0x8200, v125
	ds_write2_b32 v126, v116, v117 offset1:1
	ds_write2_b32 v126, v118, v119 offset0:2 offset1:3
	s_mov_b64 exec, s[58:59]
	s_branch .LBB0_695

.LBB0_701:
	s_cmp_lt_u32 s47, 8
	s_cbranch_scc1 .LBB0_703
	s_lshl_b32 s47, s37, 1
	s_add_u32 s47, s96, s47
	s_addc_u32 s48, s97, 0
	s_and_b64 s[38:39], exec, s[38:39]
	s_mov_b32 s38, 0xb883c00
	s_cselect_b32 s38, s38, 0xbb83a00
	v_lshlrev_b32_e32 v0, 3, v3
	s_add_u32 s38, s47, s38
	s_waitcnt vmcnt(2)
	v_and_b32_e32 v4, 56, v0
	s_addc_u32 s39, s48, 0
	v_lshlrev_b32_e32 v0, 1, v4
	v_mov_b32_e32 v1, v2
	v_or_b32_e32 v5, s37, v4
	v_ashrrev_i32_e32 v45, 3, v3
	v_lshlrev_b32_e32 v44, 2, v4
	s_movk_i32 s4, 0x104
	v_lshl_add_u64 v[0:1], s[38:39], 0, v[0:1]
	s_waitcnt vmcnt(0)
	v_lshlrev_b32_e32 v36, 2, v5
	v_mad_u64_u32 v[46:47], s[38:39], v45, s4, v[44:45]
	ds_read2_b32 v[8:9], v46 offset1:1
	v_mov_b32_e32 v4, v134
	v_mov_b32_e32 v5, v135
	v_mov_b32_e32 v6, v136
	v_mov_b32_e32 v7, v137
	v_mov_b32_e32 v26, v130
	v_mov_b32_e32 v27, v131
	v_mov_b32_e32 v28, v132
	v_mov_b32_e32 v29, v133
	ds_read2_b32 v[54:55], v46 offset0:2 offset1:3
	ds_read2_b32 v[48:49], v46 offset0:6 offset1:7
	v_mov_b32_e32 v37, v2
	s_waitcnt lgkmcnt(2)
	v_mov_b32_e32 v12, v8
	v_lshl_add_u64 v[16:17], s[40:41], 0, v[36:37]
	s_waitcnt lgkmcnt(1)
	v_mov_b32_e32 v13, v54
	v_mov_b32_e32 v54, v9
	ds_read2_b32 v[8:9], v46 offset0:4 offset1:5
	s_waitcnt lgkmcnt(1)
	v_mov_b32_e32 v51, v48
	s_movk_i32 s5, 0x2000
	v_add_co_u32_e32 v40, vcc, s5, v16
	s_waitcnt lgkmcnt(0)
	v_mov_b32_e32 v50, v8
	v_mov_b32_e32 v48, v9
	v_mov_b32_e32 v8, v174
	v_mov_b32_e32 v9, v175
	v_mov_b32_e32 v10, v176
	v_mov_b32_e32 v11, v177
	v_mov_b32_e32 v56, v170
	v_mov_b32_e32 v57, v171
	v_mov_b32_e32 v58, v172
	v_mov_b32_e32 v59, v173
	v_addc_co_u32_e32 v41, vcc, 0, v17, vcc
	v_lshl_add_u64 v[38:39], v[16:17], 0, s[22:23]
	ds_read2_b32 v[18:19], v46 offset0:65 offset1:66
	ds_read2_b32 v[24:25], v46 offset0:67 offset1:68
	s_mov_b64 s[38:39], 0x2000
	v_lshl_add_u64 v[34:35], v[16:17], 0, s[38:39]
	s_movk_i32 s37, 0x4000
	s_mov_b64 s[38:39], 0x3000
	v_lshl_add_u64 v[32:33], v[16:17], 0, s[38:39]
	v_lshl_add_u64 v[30:31], v[16:17], 0, s[0:1]
	v_add_u32_e32 v47, 0x410, v46
	v_add_u32_e32 v37, 0x420, v46
	v_add_u32_e32 v3, 0x200, v3
	v_ashrrev_i32_e32 v3, 3, v3
	s_waitcnt vmcnt(3)
	v_mov_b32_e32 v52, v4
	s_waitcnt vmcnt(2)
	v_mov_b32_e32 v14, v26
	v_mov_b32_e32 v15, v28
	v_mov_b32_e32 v53, v6
	v_mov_b32_e32 v6, v5
	v_mov_b32_e32 v28, v27
	s_waitcnt vmcnt(0)
	v_mov_b32_e32 v4, v56
	v_mov_b32_e32 v5, v58
	v_pk_fma_f32 v[4:5], v[12:13], v[14:15], v[4:5]
	v_mov_b32_e32 v12, v138
	v_mov_b32_e32 v13, v139
	v_mov_b32_e32 v14, v140
	v_mov_b32_e32 v15, v141
	v_mov_b32_e32 v20, v142
	v_mov_b32_e32 v21, v143
	v_mov_b32_e32 v22, v144
	v_mov_b32_e32 v23, v145
	v_mov_b32_e32 v58, v57
	v_pk_fma_f32 v[28:29], v[54:55], v[28:29], v[58:59]
	s_waitcnt vmcnt(1) lgkmcnt(0)
	v_pk_mul_f32 v[64:65], v[24:25], v[14:15]
	v_pk_mul_f32 v[66:67], v[18:19], v[12:13]
	v_mov_b32_e32 v13, v64
	v_mov_b32_e32 v12, v66
	v_pk_add_f32 v[4:5], v[4:5], v[12:13]
	ds_read2_b32 v[18:19], v46 offset0:130 offset1:131
	ds_read2_b32 v[42:43], v46 offset0:132 offset1:133
	v_mov_b32_e32 v12, v146
	v_mov_b32_e32 v13, v147
	v_mov_b32_e32 v14, v148
	v_mov_b32_e32 v15, v149
	v_mov_b32_e32 v24, v150
	v_mov_b32_e32 v25, v151
	v_mov_b32_e32 v26, v152
	v_mov_b32_e32 v27, v153
	ds_read2_b32 v[60:61], v46 offset0:195 offset1:196
	ds_read2_b32 v[62:63], v46 offset0:197 offset1:198
	v_mov_b32_e32 v64, v67
	v_pk_add_f32 v[28:29], v[28:29], v[64:65]
	s_waitcnt vmcnt(1) lgkmcnt(2)
	v_pk_mul_f32 v[68:69], v[42:43], v[14:15]
	v_pk_mul_f32 v[70:71], v[18:19], v[12:13]
	v_add_co_u32_e32 v42, vcc, s37, v16
	v_mov_b32_e32 v12, v70
	v_mov_b32_e32 v13, v68
	v_addc_co_u32_e32 v43, vcc, 0, v17, vcc
	v_pk_add_f32 v[4:5], v[4:5], v[12:13]
	v_mov_b32_e32 v12, v154
	v_mov_b32_e32 v13, v155
	v_mov_b32_e32 v14, v156
	v_mov_b32_e32 v15, v157
	v_mov_b32_e32 v16, v158
	v_mov_b32_e32 v17, v159
	v_mov_b32_e32 v18, v160
	v_mov_b32_e32 v19, v161
	ds_read2_b32 v[76:77], v47 offset1:1
	v_mov_b32_e32 v68, v71
	v_pk_add_f32 v[28:29], v[28:29], v[68:69]
	s_waitcnt vmcnt(1) lgkmcnt(1)
	v_pk_mul_f32 v[72:73], v[62:63], v[14:15]
	v_pk_mul_f32 v[74:75], v[60:61], v[12:13]
	v_mov_b32_e32 v13, v72
	v_mov_b32_e32 v12, v74
	v_pk_add_f32 v[4:5], v[4:5], v[12:13]
	v_add_u32_e32 v12, 0x418, v46
	ds_read2_b32 v[78:79], v12 offset1:1
	v_mov_b32_e32 v60, v162
	v_mov_b32_e32 v61, v163
	v_mov_b32_e32 v62, v164
	v_mov_b32_e32 v63, v165
	v_mov_b32_e32 v12, v166
	v_mov_b32_e32 v13, v167
	v_mov_b32_e32 v14, v168
	v_mov_b32_e32 v15, v169
	v_mov_b32_e32 v72, v75
	v_pk_add_f32 v[28:29], v[28:29], v[72:73]
	s_waitcnt vmcnt(1) lgkmcnt(0)
	v_pk_mul_f32 v[62:63], v[78:79], v[62:63]
	v_pk_mul_f32 v[60:61], v[76:77], v[60:61]
	v_mov_b32_e32 v77, v62
	v_mov_b32_e32 v62, v61
	v_mov_b32_e32 v76, v60
	v_pk_add_f32 v[54:55], v[28:29], v[62:63]
	v_pk_add_f32 v[4:5], v[4:5], v[76:77]
	v_mul_f32_e32 v28, 0xbfb8aa3b, v54
	v_mul_f32_e32 v47, 0xbfb8aa3b, v4
	v_exp_f32_e32 v58, v28
	v_mul_f32_e32 v28, 0xbfb8aa3b, v5
	v_exp_f32_e32 v56, v47
	v_exp_f32_e32 v57, v28
	s_nop 0
	v_pk_add_f32 v[56:57], v[56:57], 1.0 op_sel_hi:[1,0]
	s_nop 0
	v_div_scale_f32 v28, s[38:39], v57, v57, v5
	v_rcp_f32_e32 v29, v28
	s_nop 0
	v_fma_f32 v47, -v28, v29, 1.0
	v_fmac_f32_e32 v29, v47, v29
	v_div_scale_f32 v47, vcc, v5, v57, v5
	v_mul_f32_e32 v59, v47, v29
	v_fma_f32 v60, -v28, v59, v47
	v_fmac_f32_e32 v59, v60, v29
	v_fma_f32 v28, -v28, v59, v47
	v_div_fmas_f32 v28, v28, v29, v59
	v_div_fixup_f32 v28, v28, v57, v5
	v_div_scale_f32 v5, s[38:39], v56, v56, v4
	v_rcp_f32_e32 v29, v5
	s_nop 0
	v_fma_f32 v47, -v5, v29, 1.0
	v_fmac_f32_e32 v29, v47, v29
	v_div_scale_f32 v47, vcc, v4, v56, v4
	v_mul_f32_e32 v57, v47, v29
	v_fma_f32 v59, -v5, v57, v47
	v_fmac_f32_e32 v57, v59, v29
	v_fma_f32 v5, -v5, v57, v47
	v_div_fmas_f32 v5, v5, v29, v57
	v_div_fixup_f32 v29, v5, v56, v4
	v_mul_f32_e32 v4, 0xbfb8aa3b, v55
	v_exp_f32_e32 v59, v4
	s_nop 0
	v_pk_add_f32 v[4:5], v[58:59], 1.0 op_sel_hi:[1,0]
	s_nop 0
	v_div_scale_f32 v47, s[38:39], v4, v4, v54
	v_rcp_f32_e32 v56, v47
	s_nop 0
	v_fma_f32 v57, -v47, v56, 1.0
	v_fmac_f32_e32 v56, v57, v56
	v_div_scale_f32 v57, vcc, v54, v4, v54
	v_mul_f32_e32 v58, v57, v56
	v_fma_f32 v59, -v47, v58, v57
	v_fmac_f32_e32 v58, v59, v56
	v_fma_f32 v47, -v47, v58, v57
	v_div_fmas_f32 v47, v47, v56, v58
	v_div_fixup_f32 v47, v47, v4, v54
	v_div_scale_f32 v4, s[38:39], v5, v5, v55
	v_rcp_f32_e32 v54, v4
	s_nop 0
	v_fma_f32 v56, -v4, v54, 1.0
	v_fmac_f32_e32 v54, v56, v54
	v_div_scale_f32 v56, vcc, v55, v5, v55
	v_mul_f32_e32 v57, v56, v54
	v_fma_f32 v58, -v4, v57, v56
	v_fmac_f32_e32 v57, v58, v54
	v_fma_f32 v4, -v4, v57, v56
	v_div_fmas_f32 v4, v4, v54, v57
	v_div_fixup_f32 v54, v4, v5, v55
	v_mov_b32_e32 v4, v8
	v_mov_b32_e32 v5, v10
	v_pk_fma_f32 v[4:5], v[50:51], v[52:53], v[4:5]
	ds_read2_b32 v[50:51], v46 offset0:69 offset1:70
	ds_read2_b32 v[52:53], v46 offset0:71 offset1:72
	v_add_u32_e32 v8, 0x428, v46
	v_mov_b32_e32 v10, v9
	v_pk_fma_f32 v[6:7], v[48:49], v[6:7], v[10:11]
	s_waitcnt lgkmcnt(1)
	v_pk_mul_f32 v[20:21], v[50:51], v[20:21]
	s_waitcnt lgkmcnt(0)
	v_pk_mul_f32 v[22:23], v[52:53], v[22:23]
	v_mov_b32_e32 v50, v20
	v_mov_b32_e32 v51, v22
	v_pk_add_f32 v[4:5], v[4:5], v[50:51]
	ds_read2_b32 v[50:51], v46 offset0:134 offset1:135
	ds_read2_b32 v[52:53], v46 offset0:136 offset1:137
	v_mov_b32_e32 v22, v21
	v_pk_add_f32 v[6:7], v[6:7], v[22:23]
	s_waitcnt lgkmcnt(1)
	v_pk_mul_f32 v[24:25], v[50:51], v[24:25]
	s_waitcnt lgkmcnt(0)
	v_pk_mul_f32 v[26:27], v[52:53], v[26:27]
	v_mov_b32_e32 v50, v24
	v_mov_b32_e32 v51, v26
	v_pk_add_f32 v[4:5], v[4:5], v[50:51]
	ds_read2_b32 v[50:51], v46 offset0:199 offset1:200
	ds_read2_b32 v[52:53], v46 offset0:201 offset1:202
	v_mov_b32_e32 v26, v25
	v_pk_add_f32 v[6:7], v[6:7], v[26:27]
	s_waitcnt lgkmcnt(1)
	v_pk_mul_f32 v[16:17], v[50:51], v[16:17]
	s_waitcnt lgkmcnt(0)
	v_pk_mul_f32 v[18:19], v[52:53], v[18:19]
	v_mov_b32_e32 v50, v16
	v_mov_b32_e32 v51, v18
	v_pk_add_f32 v[4:5], v[4:5], v[50:51]
	ds_read2_b32 v[50:51], v37 offset1:1
	ds_read2_b32 v[52:53], v8 offset1:1
	v_mov_b32_e32 v18, v17
	v_pk_add_f32 v[6:7], v[6:7], v[18:19]
	s_waitcnt vmcnt(0) lgkmcnt(1)
	v_pk_mul_f32 v[12:13], v[50:51], v[12:13]
	s_waitcnt lgkmcnt(0)
	v_pk_mul_f32 v[14:15], v[52:53], v[14:15]
	v_mov_b32_e32 v50, v12
	v_mov_b32_e32 v51, v14
	v_mov_b32_e32 v14, v13
	v_pk_add_f32 v[6:7], v[6:7], v[14:15]
	v_pk_add_f32 v[4:5], v[4:5], v[50:51]
	v_mul_f32_e32 v9, 0xbfb8aa3b, v6
	v_mul_f32_e32 v8, 0xbfb8aa3b, v4
	v_exp_f32_e32 v10, v9
	v_mul_f32_e32 v9, 0xbfb8aa3b, v5
	v_exp_f32_e32 v8, v8
	v_exp_f32_e32 v9, v9
	s_nop 0
	v_pk_add_f32 v[8:9], v[8:9], 1.0 op_sel_hi:[1,0]
	s_nop 0
	v_div_scale_f32 v11, s[38:39], v9, v9, v5
	v_rcp_f32_e32 v12, v11
	s_nop 0
	v_fma_f32 v13, -v11, v12, 1.0
	v_fmac_f32_e32 v12, v13, v12
	v_div_scale_f32 v13, vcc, v5, v9, v5
	v_mul_f32_e32 v14, v13, v12
	v_fma_f32 v15, -v11, v14, v13
	v_fmac_f32_e32 v14, v15, v12
	v_fma_f32 v11, -v11, v14, v13
	v_div_fmas_f32 v11, v11, v12, v14
	v_div_fixup_f32 v9, v11, v9, v5
	v_div_scale_f32 v5, s[38:39], v8, v8, v4
	v_rcp_f32_e32 v11, v5
	s_nop 0
	v_fma_f32 v12, -v5, v11, 1.0
	v_fmac_f32_e32 v11, v12, v11
	v_div_scale_f32 v12, vcc, v4, v8, v4
	v_mul_f32_e32 v13, v12, v11
	v_fma_f32 v14, -v5, v13, v12
	v_fmac_f32_e32 v13, v14, v11
	v_fma_f32 v5, -v5, v13, v12
	v_div_fmas_f32 v5, v5, v11, v13
	v_div_fixup_f32 v8, v5, v8, v4
	v_mul_f32_e32 v4, 0xbfb8aa3b, v7
	v_exp_f32_e32 v11, v4
	s_nop 0
	v_pk_add_f32 v[4:5], v[10:11], 1.0 op_sel_hi:[1,0]
	s_nop 0
	v_div_scale_f32 v10, s[38:39], v4, v4, v6
	v_rcp_f32_e32 v11, v10
	s_nop 0
	v_fma_f32 v12, -v10, v11, 1.0
	v_fmac_f32_e32 v11, v12, v11
	v_div_scale_f32 v12, vcc, v6, v4, v6
	v_mul_f32_e32 v13, v12, v11
	v_fma_f32 v14, -v10, v13, v12
	v_fmac_f32_e32 v13, v14, v11
	v_fma_f32 v10, -v10, v13, v12
	v_div_fmas_f32 v10, v10, v11, v13
	v_div_fixup_f32 v4, v10, v4, v6
	v_div_scale_f32 v6, s[38:39], v5, v5, v7
	v_rcp_f32_e32 v10, v6
	s_nop 0
	v_fma_f32 v11, -v6, v10, 1.0
	v_fmac_f32_e32 v10, v11, v10
	v_div_scale_f32 v11, vcc, v7, v5, v7
	v_mul_f32_e32 v12, v11, v10
	v_fma_f32 v13, -v6, v12, v11
	v_fmac_f32_e32 v12, v13, v10
	v_fma_f32 v6, -v6, v12, v11
	v_div_fmas_f32 v6, v6, v10, v12
	v_div_fixup_f32 v5, v6, v5, v7
	v_bfe_u32 v10, v5, 16, 1
	v_bfe_u32 v11, v4, 16, 1
	v_add3_u32 v10, v5, v10, s27
	v_bfe_u32 v5, v28, 16, 1
	v_bfe_u32 v12, v8, 16, 1
	v_bfe_u32 v6, v54, 16, 1
	v_add3_u32 v11, v4, v11, s27
	v_bfe_u32 v4, v29, 16, 1
	v_bfe_u32 v13, v9, 16, 1
	v_add3_u32 v5, v28, v5, s27
	v_add3_u32 v8, v8, v12, s27
	v_bfe_u32 v7, v47, 16, 1
	v_add3_u32 v6, v54, v6, s27
	v_add3_u32 v4, v29, v4, s27
	v_add3_u32 v9, v9, v13, s27
	v_lshrrev_b32_e32 v5, 16, v5
	v_lshrrev_b32_e32 v8, 16, v8
	v_add3_u32 v7, v47, v7, s27
	v_lshrrev_b32_e32 v4, 16, v4
	v_lshrrev_b32_e32 v9, 16, v9
	v_and_or_b32 v5, v6, s28, v5
	v_and_or_b32 v6, v11, s28, v8
	v_add_u32_e32 v8, s35, v45
	v_and_or_b32 v4, v7, s28, v4
	v_and_or_b32 v7, v10, s28, v9
	v_ashrrev_i32_e32 v9, 31, v8
	v_lshlrev_b64 v[8:9], 9, v[8:9]
	v_lshl_add_u64 v[8:9], v[0:1], 0, v[8:9]
	global_store_dwordx4 v[8:9], v[4:7], off
	v_mad_u64_u32 v[28:29], s[38:39], v3, s4, v[44:45]
	ds_read2_b32 v[8:9], v28 offset1:1
	v_mov_b32_e32 v4, v134
	v_mov_b32_e32 v5, v135
	v_mov_b32_e32 v6, v136
	v_mov_b32_e32 v7, v137
	v_mov_b32_e32 v48, v130
	v_mov_b32_e32 v49, v131
	v_mov_b32_e32 v50, v132
	v_mov_b32_e32 v51, v133
	ds_read2_b32 v[56:57], v28 offset0:2 offset1:3
	ds_read2_b32 v[44:45], v28 offset0:6 offset1:7
	v_add_u32_e32 v29, 0x410, v28
	s_waitcnt lgkmcnt(2)
	v_mov_b32_e32 v12, v8
	v_add_u32_e32 v37, 0x420, v28
	s_waitcnt lgkmcnt(1)
	v_mov_b32_e32 v13, v56
	v_mov_b32_e32 v56, v9
	ds_read2_b32 v[8:9], v28 offset0:4 offset1:5
	s_waitcnt lgkmcnt(1)
	v_mov_b32_e32 v47, v44
	s_waitcnt lgkmcnt(0)
	v_mov_b32_e32 v46, v8
	v_mov_b32_e32 v44, v9
	v_mov_b32_e32 v8, v174
	v_mov_b32_e32 v9, v175
	v_mov_b32_e32 v10, v176
	v_mov_b32_e32 v11, v177
	v_mov_b32_e32 v52, v170
	v_mov_b32_e32 v53, v171
	v_mov_b32_e32 v54, v172
	v_mov_b32_e32 v55, v173
	ds_read2_b32 v[16:17], v28 offset0:65 offset1:66
	ds_read2_b32 v[18:19], v28 offset0:67 offset1:68
	s_waitcnt vmcnt(2)
	v_mov_b32_e32 v14, v48
	v_mov_b32_e32 v15, v50
	v_mov_b32_e32 v50, v49
	v_mov_b32_e32 v48, v4
	v_mov_b32_e32 v49, v6
	v_mov_b32_e32 v6, v5
	s_waitcnt vmcnt(0)
	v_mov_b32_e32 v4, v52
	v_mov_b32_e32 v5, v54
	v_pk_fma_f32 v[4:5], v[12:13], v[14:15], v[4:5]
	v_mov_b32_e32 v12, v138
	v_mov_b32_e32 v13, v139
	v_mov_b32_e32 v14, v140
	v_mov_b32_e32 v15, v141
	v_mov_b32_e32 v24, v142
	v_mov_b32_e32 v25, v143
	v_mov_b32_e32 v26, v144
	v_mov_b32_e32 v27, v145
	v_mov_b32_e32 v54, v53
	s_waitcnt vmcnt(1) lgkmcnt(0)
	v_pk_mul_f32 v[38:39], v[18:19], v[14:15]
	v_pk_mul_f32 v[58:59], v[16:17], v[12:13]
	v_mov_b32_e32 v13, v38
	v_mov_b32_e32 v12, v58
	v_pk_add_f32 v[4:5], v[4:5], v[12:13]
	ds_read2_b32 v[16:17], v28 offset0:130 offset1:131
	ds_read2_b32 v[18:19], v28 offset0:132 offset1:133
	v_mov_b32_e32 v12, v146
	v_mov_b32_e32 v13, v147
	v_mov_b32_e32 v14, v148
	v_mov_b32_e32 v15, v149
	v_mov_b32_e32 v20, v150
	v_mov_b32_e32 v21, v151
	v_mov_b32_e32 v22, v152
	v_mov_b32_e32 v23, v153
	ds_read2_b32 v[34:35], v28 offset0:195 offset1:196
	ds_read2_b32 v[62:63], v28 offset0:197 offset1:198
	v_mov_b32_e32 v38, v59
	s_waitcnt vmcnt(1) lgkmcnt(2)
	v_pk_mul_f32 v[40:41], v[18:19], v[14:15]
	v_pk_mul_f32 v[60:61], v[16:17], v[12:13]
	v_mov_b32_e32 v13, v40
	v_mov_b32_e32 v12, v60
	v_pk_add_f32 v[4:5], v[4:5], v[12:13]
	v_mov_b32_e32 v12, v154
	v_mov_b32_e32 v13, v155
	v_mov_b32_e32 v14, v156
	v_mov_b32_e32 v15, v157
	v_mov_b32_e32 v16, v158
	v_mov_b32_e32 v17, v159
	v_mov_b32_e32 v18, v160
	v_mov_b32_e32 v19, v161
	ds_read2_b32 v[66:67], v29 offset1:1
	v_mov_b32_e32 v40, v61
	s_waitcnt vmcnt(1) lgkmcnt(1)
	v_pk_mul_f32 v[62:63], v[62:63], v[14:15]
	v_pk_mul_f32 v[64:65], v[34:35], v[12:13]
	v_mov_b32_e32 v13, v62
	v_mov_b32_e32 v12, v64
	v_pk_add_f32 v[4:5], v[4:5], v[12:13]
	v_add_u32_e32 v12, 0x418, v28
	ds_read2_b32 v[68:69], v12 offset1:1
	v_mov_b32_e32 v32, v162
	v_mov_b32_e32 v33, v163
	v_mov_b32_e32 v34, v164
	v_mov_b32_e32 v35, v165
	v_mov_b32_e32 v12, v166
	v_mov_b32_e32 v13, v167
	v_mov_b32_e32 v14, v168
	v_mov_b32_e32 v15, v169
	v_mov_b32_e32 v62, v65
	s_waitcnt vmcnt(1) lgkmcnt(0)
	v_pk_mul_f32 v[30:31], v[68:69], v[34:35]
	v_pk_mul_f32 v[32:33], v[66:67], v[32:33]
	v_mov_b32_e32 v35, v30
	v_mov_b32_e32 v34, v32
	v_pk_add_f32 v[4:5], v[4:5], v[34:35]
	v_pk_fma_f32 v[34:35], v[56:57], v[50:51], v[54:55]
	v_mov_b32_e32 v30, v33
	v_pk_add_f32 v[34:35], v[34:35], v[38:39]
	v_mul_f32_e32 v29, 0xbfb8aa3b, v4
	v_pk_add_f32 v[34:35], v[34:35], v[40:41]
	v_exp_f32_e32 v32, v29
	v_pk_add_f32 v[34:35], v[34:35], v[62:63]
	s_nop 0
	v_pk_add_f32 v[30:31], v[34:35], v[30:31]
	s_nop 0
	v_mul_f32_e32 v29, 0xbfb8aa3b, v30
	v_exp_f32_e32 v34, v29
	v_mul_f32_e32 v29, 0xbfb8aa3b, v5
	v_exp_f32_e32 v33, v29
	s_nop 0
	v_pk_add_f32 v[32:33], v[32:33], 1.0 op_sel_hi:[1,0]
	s_nop 0
	v_div_scale_f32 v29, s[38:39], v33, v33, v5
	v_rcp_f32_e32 v35, v29
	s_nop 0
	v_fma_f32 v36, -v29, v35, 1.0
	v_fmac_f32_e32 v35, v36, v35
	v_div_scale_f32 v36, vcc, v5, v33, v5
	v_mul_f32_e32 v38, v36, v35
	v_fma_f32 v39, -v29, v38, v36
	v_fmac_f32_e32 v38, v39, v35
	v_fma_f32 v29, -v29, v38, v36
	v_div_fmas_f32 v29, v29, v35, v38
	v_div_fixup_f32 v29, v29, v33, v5
	v_div_scale_f32 v5, s[38:39], v32, v32, v4
	v_rcp_f32_e32 v33, v5
	s_nop 0
	v_fma_f32 v35, -v5, v33, 1.0
	v_fmac_f32_e32 v33, v35, v33
	v_div_scale_f32 v35, vcc, v4, v32, v4
	v_mul_f32_e32 v36, v35, v33
	v_fma_f32 v38, -v5, v36, v35
	v_fmac_f32_e32 v36, v38, v33
	v_fma_f32 v5, -v5, v36, v35
	v_div_fmas_f32 v5, v5, v33, v36
	v_div_fixup_f32 v32, v5, v32, v4
	v_mul_f32_e32 v4, 0xbfb8aa3b, v31
	v_exp_f32_e32 v35, v4
	s_nop 0
	v_pk_add_f32 v[4:5], v[34:35], 1.0 op_sel_hi:[1,0]
	s_nop 0
	v_div_scale_f32 v33, s[38:39], v4, v4, v30
	v_rcp_f32_e32 v34, v33
	s_nop 0
	v_fma_f32 v35, -v33, v34, 1.0
	v_fmac_f32_e32 v34, v35, v34
	v_div_scale_f32 v35, vcc, v30, v4, v30
	v_mul_f32_e32 v36, v35, v34
	v_fma_f32 v38, -v33, v36, v35
	v_fmac_f32_e32 v36, v38, v34
	v_fma_f32 v33, -v33, v36, v35
	v_div_fmas_f32 v33, v33, v34, v36
	v_div_fixup_f32 v33, v33, v4, v30
	v_div_scale_f32 v4, s[38:39], v5, v5, v31
	v_rcp_f32_e32 v30, v4
	s_nop 0
	v_fma_f32 v34, -v4, v30, 1.0
	v_fmac_f32_e32 v30, v34, v30
	v_div_scale_f32 v34, vcc, v31, v5, v31
	v_mul_f32_e32 v35, v34, v30
	v_fma_f32 v36, -v4, v35, v34
	v_fmac_f32_e32 v35, v36, v30
	v_fma_f32 v4, -v4, v35, v34
	v_div_fmas_f32 v4, v4, v30, v35
	v_div_fixup_f32 v34, v4, v5, v31
	v_mov_b32_e32 v4, v8
	v_mov_b32_e32 v5, v10
	v_pk_fma_f32 v[30:31], v[46:47], v[48:49], v[4:5]
	ds_read2_b32 v[38:39], v28 offset0:69 offset1:70
	ds_read2_b32 v[4:5], v28 offset0:71 offset1:72
	v_mov_b32_e32 v10, v9
	v_pk_fma_f32 v[6:7], v[44:45], v[6:7], v[10:11]
	s_waitcnt lgkmcnt(1)
	v_pk_mul_f32 v[24:25], v[38:39], v[24:25]
	s_waitcnt lgkmcnt(0)
	v_pk_mul_f32 v[4:5], v[4:5], v[26:27]
	v_mov_b32_e32 v26, v24
	v_mov_b32_e32 v27, v4
	v_pk_add_f32 v[26:27], v[30:31], v[26:27]
	ds_read2_b32 v[30:31], v28 offset0:134 offset1:135
	ds_read2_b32 v[38:39], v28 offset0:136 offset1:137
	v_add_u32_e32 v4, 0x428, v28
	s_waitcnt lgkmcnt(1)
	v_pk_mul_f32 v[20:21], v[30:31], v[20:21]
	s_waitcnt lgkmcnt(0)
	v_pk_mul_f32 v[22:23], v[38:39], v[22:23]
	v_mov_b32_e32 v30, v20
	v_mov_b32_e32 v31, v22
	v_pk_add_f32 v[26:27], v[26:27], v[30:31]
	ds_read2_b32 v[30:31], v28 offset0:199 offset1:200
	ds_read2_b32 v[38:39], v28 offset0:201 offset1:202
	v_mov_b32_e32 v22, v21
	s_waitcnt lgkmcnt(1)
	v_pk_mul_f32 v[16:17], v[30:31], v[16:17]
	s_waitcnt lgkmcnt(0)
	v_pk_mul_f32 v[18:19], v[38:39], v[18:19]
	v_mov_b32_e32 v30, v16
	v_mov_b32_e32 v31, v18
	v_pk_add_f32 v[26:27], v[26:27], v[30:31]
	ds_read2_b32 v[30:31], v37 offset1:1
	ds_read2_b32 v[36:37], v4 offset1:1
	v_mov_b32_e32 v18, v17
	s_waitcnt vmcnt(0) lgkmcnt(1)
	v_pk_mul_f32 v[12:13], v[30:31], v[12:13]
	s_waitcnt lgkmcnt(0)
	v_pk_mul_f32 v[14:15], v[36:37], v[14:15]
	v_mov_b32_e32 v30, v12
	v_mov_b32_e32 v31, v14
	v_pk_add_f32 v[26:27], v[26:27], v[30:31]
	v_mov_b32_e32 v14, v13
	v_mul_f32_e32 v4, 0xbfb8aa3b, v26
	v_exp_f32_e32 v8, v4
	v_mov_b32_e32 v4, v25
	v_pk_add_f32 v[4:5], v[6:7], v[4:5]
	v_mul_f32_e32 v7, 0xbfb8aa3b, v27
	v_exp_f32_e32 v9, v7
	v_pk_add_f32 v[4:5], v[4:5], v[22:23]
	v_pk_add_f32 v[8:9], v[8:9], 1.0 op_sel_hi:[1,0]
	s_nop 0
	v_div_scale_f32 v7, s[38:39], v9, v9, v27
	v_rcp_f32_e32 v10, v7
	v_pk_add_f32 v[4:5], v[4:5], v[18:19]
	v_fma_f32 v11, -v7, v10, 1.0
	v_fmac_f32_e32 v10, v11, v10
	v_div_scale_f32 v11, vcc, v27, v9, v27
	v_mul_f32_e32 v12, v11, v10
	v_fma_f32 v13, -v7, v12, v11
	v_fmac_f32_e32 v12, v13, v10
	v_fma_f32 v7, -v7, v12, v11
	v_div_fmas_f32 v7, v7, v10, v12
	v_div_fixup_f32 v9, v7, v9, v27
	v_div_scale_f32 v7, s[38:39], v8, v8, v26
	v_rcp_f32_e32 v10, v7
	v_pk_add_f32 v[4:5], v[4:5], v[14:15]
	v_fma_f32 v11, -v7, v10, 1.0
	v_fmac_f32_e32 v10, v11, v10
	v_div_scale_f32 v11, vcc, v26, v8, v26
	v_mul_f32_e32 v12, v11, v10
	v_fma_f32 v13, -v7, v12, v11
	v_fmac_f32_e32 v12, v13, v10
	v_fma_f32 v7, -v7, v12, v11
	v_div_fmas_f32 v7, v7, v10, v12
	v_mul_f32_e32 v6, 0xbfb8aa3b, v4
	v_div_fixup_f32 v8, v7, v8, v26
	v_mul_f32_e32 v7, 0xbfb8aa3b, v5
	v_exp_f32_e32 v6, v6
	v_exp_f32_e32 v7, v7
	s_nop 0
	v_pk_add_f32 v[6:7], v[6:7], 1.0 op_sel_hi:[1,0]
	s_nop 0
	v_div_scale_f32 v10, s[38:39], v6, v6, v4
	v_rcp_f32_e32 v11, v10
	s_nop 0
	v_fma_f32 v12, -v10, v11, 1.0
	v_fmac_f32_e32 v11, v12, v11
	v_div_scale_f32 v12, vcc, v4, v6, v4
	v_mul_f32_e32 v13, v12, v11
	v_fma_f32 v14, -v10, v13, v12
	v_fmac_f32_e32 v13, v14, v11
	v_fma_f32 v10, -v10, v13, v12
	v_div_fmas_f32 v10, v10, v11, v13
	v_div_fixup_f32 v4, v10, v6, v4
	v_div_scale_f32 v6, s[38:39], v7, v7, v5
	v_rcp_f32_e32 v10, v6
	s_nop 0
	v_fma_f32 v11, -v6, v10, 1.0
	v_fmac_f32_e32 v10, v11, v10
	v_div_scale_f32 v11, vcc, v5, v7, v5
	v_mul_f32_e32 v12, v11, v10
	v_fma_f32 v13, -v6, v12, v11
	v_fmac_f32_e32 v12, v13, v10
	v_fma_f32 v6, -v6, v12, v11
	v_div_fmas_f32 v6, v6, v10, v12
	v_div_fixup_f32 v5, v6, v7, v5
	v_bfe_u32 v10, v5, 16, 1
	v_bfe_u32 v11, v4, 16, 1
	v_add3_u32 v10, v5, v10, s27
	v_bfe_u32 v5, v29, 16, 1
	v_bfe_u32 v12, v8, 16, 1
	v_bfe_u32 v6, v34, 16, 1
	v_add3_u32 v11, v4, v11, s27
	v_bfe_u32 v4, v32, 16, 1
	v_bfe_u32 v13, v9, 16, 1
	v_add3_u32 v5, v29, v5, s27
	v_add3_u32 v8, v8, v12, s27
	v_bfe_u32 v7, v33, 16, 1
	v_add3_u32 v6, v34, v6, s27
	v_add3_u32 v4, v32, v4, s27
	v_add3_u32 v9, v9, v13, s27
	v_lshrrev_b32_e32 v5, 16, v5
	v_lshrrev_b32_e32 v8, 16, v8
	v_add3_u32 v7, v33, v7, s27
	v_lshrrev_b32_e32 v4, 16, v4
	v_lshrrev_b32_e32 v9, 16, v9
	v_and_or_b32 v5, v6, s28, v5
	v_and_or_b32 v6, v11, s28, v8
	v_add_u32_e32 v8, s35, v3
	v_and_or_b32 v4, v7, s28, v4
	v_and_or_b32 v7, v10, s28, v9
	v_ashrrev_i32_e32 v9, 31, v8
	v_lshlrev_b64 v[8:9], 9, v[8:9]
	v_lshl_add_u64 v[0:1], v[0:1], 0, v[8:9]
	global_store_dwordx4 v[0:1], v[4:7], off
